# v4 + removed the 8 redundant mid-segment s_setprio 0/1 flip pairs in GEMM MMA segments
# speedup vs baseline: 1.0035x; 1.0019x over previous
.Lk_peel:
	s_add_i32 s44, s14, 2
	s_add_u32 s45, s0, 0x80
	s_addc_u32 s15, s1, 0
	s_add_i32 s57, 0, 0x10000
	s_cmp_eq_u32 s18, s14
	s_cselect_b32 s15, s89, s15
	s_cselect_b32 s14, s88, s45
	s_cselect_b32 vcc_hi, s11, s43
	s_cselect_b32 vcc_lo, s10, s42
	s_add_i32 s45, 0, 0x14000
	s_waitcnt lgkmcnt(0)
	ds_read_b128 v[130:133], v248
	ds_read_b128 v[134:137], v248 offset:1024
	ds_read_b128 v[138:141], v248 offset:2048
	ds_read_b128 v[142:145], v248 offset:3072
	ds_read_b128 v[146:149], v248 offset:16384
	ds_read_b128 v[150:153], v248 offset:17408
	ds_read_b128 v[154:157], v248 offset:18432
	ds_read_b128 v[158:161], v248 offset:19456
	s_add_i32 m0, s70, 0xc000
	ds_read_b128 v[162:165], v237
	ds_read_b128 v[166:169], v237 offset:1024
	ds_read_b128 v[184:187], v237 offset:2048
	ds_read_b128 v[188:191], v237 offset:3072
	ds_read_b128 v[192:195], v237 offset:4096
	ds_read_b128 v[196:199], v237 offset:5120
	ds_read_b128 v[200:203], v237 offset:6144
	ds_read_b128 v[214:217], v237 offset:7168
	global_load_lds_dwordx4 v180, s[0:1]
	s_add_i32 m0, s70, 0xe000
	s_nop 0
	global_load_lds_dwordx4 v182, s[0:1]
	s_waitcnt vmcnt(8)
	s_waitcnt lgkmcnt(0)
	s_barrier
	s_setprio 1
	s_waitcnt lgkmcnt(0)
	v_mfma_f32_16x16x32_bf16 v[122:125], v[130:133], v[162:165], 0
	v_mfma_f32_16x16x32_bf16 v[126:129], v[138:141], v[162:165], 0
	v_mfma_f32_16x16x32_bf16 v[106:109], v[130:133], v[184:187], 0
	v_mfma_f32_16x16x32_bf16 v[110:113], v[138:141], v[184:187], 0
	v_mfma_f32_16x16x32_bf16 v[90:93], v[130:133], v[192:195], 0
	v_mfma_f32_16x16x32_bf16 v[94:97], v[138:141], v[192:195], 0
	v_mfma_f32_16x16x32_bf16 v[74:77], v[130:133], v[200:203], 0
	v_mfma_f32_16x16x32_bf16 v[78:81], v[138:141], v[200:203], 0
	v_mfma_f32_16x16x32_bf16 v[122:125], v[134:137], v[166:169], v[122:125]
	v_mfma_f32_16x16x32_bf16 v[126:129], v[142:145], v[166:169], v[126:129]
	v_mfma_f32_16x16x32_bf16 v[106:109], v[134:137], v[188:191], v[106:109]
	v_mfma_f32_16x16x32_bf16 v[110:113], v[142:145], v[188:191], v[110:113]
	v_mfma_f32_16x16x32_bf16 v[90:93], v[134:137], v[196:199], v[90:93]
	v_mfma_f32_16x16x32_bf16 v[94:97], v[142:145], v[196:199], v[94:97]
	v_mfma_f32_16x16x32_bf16 v[74:77], v[134:137], v[214:217], v[74:77]
	v_mfma_f32_16x16x32_bf16 v[78:81], v[142:145], v[214:217], v[78:81]
	v_mfma_f32_16x16x32_bf16 v[114:117], v[146:149], v[162:165], 0
	v_mfma_f32_16x16x32_bf16 v[118:121], v[154:157], v[162:165], 0
	v_mfma_f32_16x16x32_bf16 v[98:101], v[146:149], v[184:187], 0
	v_mfma_f32_16x16x32_bf16 v[102:105], v[154:157], v[184:187], 0
	v_mfma_f32_16x16x32_bf16 v[82:85], v[146:149], v[192:195], 0
	v_mfma_f32_16x16x32_bf16 v[86:89], v[154:157], v[192:195], 0
	v_mfma_f32_16x16x32_bf16 v[66:69], v[146:149], v[200:203], 0
	v_mfma_f32_16x16x32_bf16 v[70:73], v[154:157], v[200:203], 0
	v_mfma_f32_16x16x32_bf16 v[114:117], v[150:153], v[166:169], v[114:117]
	v_mfma_f32_16x16x32_bf16 v[118:121], v[158:161], v[166:169], v[118:121]
	v_mfma_f32_16x16x32_bf16 v[98:101], v[150:153], v[188:191], v[98:101]
	v_mfma_f32_16x16x32_bf16 v[102:105], v[158:161], v[188:191], v[102:105]
	v_mfma_f32_16x16x32_bf16 v[82:85], v[150:153], v[196:199], v[82:85]
	v_mfma_f32_16x16x32_bf16 v[86:89], v[158:161], v[196:199], v[86:89]
	v_mfma_f32_16x16x32_bf16 v[66:69], v[150:153], v[214:217], v[66:69]
	v_mfma_f32_16x16x32_bf16 v[70:73], v[158:161], v[214:217], v[70:73]
	s_setprio 0
	s_barrier
	s_add_i32 s57, s57, s59
	s_mov_b32 m0, s57
	ds_read_b128 v[162:165], v237 offset:16384
	ds_read_b128 v[166:169], v237 offset:17408
	ds_read_b128 v[184:187], v237 offset:18432
	ds_read_b128 v[188:191], v237 offset:19456
	ds_read_b128 v[192:195], v237 offset:20480
	ds_read_b128 v[196:199], v237 offset:21504
	ds_read_b128 v[200:203], v237 offset:22528
	ds_read_b128 v[214:217], v237 offset:23552
	global_load_lds_dwordx4 v0, vcc
	s_add_i32 m0, s57, 0x2000
	s_add_i32 s45, s45, s59
	global_load_lds_dwordx4 v176, vcc
	s_mov_b32 m0, s45
	s_nop 0
	global_load_lds_dwordx4 v242, vcc
	s_add_i32 m0, s45, 0x2000
	s_nop 0
	global_load_lds_dwordx4 v249, vcc
	s_mov_b32 m0, s70
	s_nop 0
	global_load_lds_dwordx4 v172, s[14:15]
	s_mov_b32 m0, s4
	s_nop 0
	global_load_lds_dwordx4 v174, s[14:15]
	s_waitcnt vmcnt(8)
	s_waitcnt lgkmcnt(0)
	s_barrier
	s_setprio 1
	s_waitcnt lgkmcnt(0)
	v_mfma_f32_16x16x32_bf16 v[58:61], v[130:133], v[162:165], 0
	v_mfma_f32_16x16x32_bf16 v[62:65], v[138:141], v[162:165], 0
	v_mfma_f32_16x16x32_bf16 v[42:45], v[130:133], v[184:187], 0
	v_mfma_f32_16x16x32_bf16 v[46:49], v[138:141], v[184:187], 0
	v_mfma_f32_16x16x32_bf16 v[26:29], v[130:133], v[192:195], 0
	v_mfma_f32_16x16x32_bf16 v[30:33], v[138:141], v[192:195], 0
	v_mfma_f32_16x16x32_bf16 v[10:13], v[130:133], v[200:203], 0
	v_mfma_f32_16x16x32_bf16 v[14:17], v[138:141], v[200:203], 0
	v_mfma_f32_16x16x32_bf16 v[58:61], v[134:137], v[166:169], v[58:61]
	v_mfma_f32_16x16x32_bf16 v[62:65], v[142:145], v[166:169], v[62:65]
	v_mfma_f32_16x16x32_bf16 v[42:45], v[134:137], v[188:191], v[42:45]
	v_mfma_f32_16x16x32_bf16 v[46:49], v[142:145], v[188:191], v[46:49]
	v_mfma_f32_16x16x32_bf16 v[26:29], v[134:137], v[196:199], v[26:29]
	v_mfma_f32_16x16x32_bf16 v[30:33], v[142:145], v[196:199], v[30:33]
	v_mfma_f32_16x16x32_bf16 v[10:13], v[134:137], v[214:217], v[10:13]
	v_mfma_f32_16x16x32_bf16 v[14:17], v[142:145], v[214:217], v[14:17]
	v_mfma_f32_16x16x32_bf16 v[50:53], v[146:149], v[162:165], 0
	v_mfma_f32_16x16x32_bf16 v[54:57], v[154:157], v[162:165], 0
	v_mfma_f32_16x16x32_bf16 v[34:37], v[146:149], v[184:187], 0
	v_mfma_f32_16x16x32_bf16 v[38:41], v[154:157], v[184:187], 0
	v_mfma_f32_16x16x32_bf16 v[18:21], v[146:149], v[192:195], 0
	v_mfma_f32_16x16x32_bf16 v[22:25], v[154:157], v[192:195], 0
	v_mfma_f32_16x16x32_bf16 v[6:9], v[146:149], v[200:203], 0
	v_mfma_f32_16x16x32_bf16 v[2:5], v[154:157], v[200:203], 0
	v_mfma_f32_16x16x32_bf16 v[50:53], v[150:153], v[166:169], v[50:53]
	v_mfma_f32_16x16x32_bf16 v[54:57], v[158:161], v[166:169], v[54:57]
	v_mfma_f32_16x16x32_bf16 v[34:37], v[150:153], v[188:191], v[34:37]
	v_mfma_f32_16x16x32_bf16 v[38:41], v[158:161], v[188:191], v[38:41]
	v_mfma_f32_16x16x32_bf16 v[18:21], v[150:153], v[196:199], v[18:21]
	v_mfma_f32_16x16x32_bf16 v[22:25], v[158:161], v[196:199], v[22:25]
	v_mfma_f32_16x16x32_bf16 v[6:9], v[150:153], v[214:217], v[6:9]
	v_mfma_f32_16x16x32_bf16 v[2:5], v[158:161], v[214:217], v[2:5]
	s_setprio 0
	s_barrier
	s_add_i32 s45, 0, 0x18000
	s_add_i32 s57, 0, 0x1c000
	ds_read_b128 v[130:133], v248 offset:32768
	ds_read_b128 v[134:137], v248 offset:33792
	ds_read_b128 v[138:141], v248 offset:34816
	ds_read_b128 v[142:145], v248 offset:35840
	ds_read_b128 v[146:149], v248 offset:49152
	ds_read_b128 v[150:153], v248 offset:50176
	ds_read_b128 v[154:157], v248 offset:51200
	ds_read_b128 v[158:161], v248 offset:52224
	s_mov_b32 m0, s63
	ds_read_b128 v[162:165], v237 offset:32768
	ds_read_b128 v[166:169], v237 offset:33792
	ds_read_b128 v[184:187], v237 offset:34816
	ds_read_b128 v[188:191], v237 offset:35840
	ds_read_b128 v[192:195], v237 offset:36864
	ds_read_b128 v[196:199], v237 offset:37888
	ds_read_b128 v[200:203], v237 offset:38912
	ds_read_b128 v[214:217], v237 offset:39936
	global_load_lds_dwordx4 v180, s[14:15]
	s_mov_b32 m0, s68
	s_nop 0
	global_load_lds_dwordx4 v182, s[14:15]
	s_waitcnt vmcnt(8)
	s_waitcnt lgkmcnt(0)
	s_barrier
	s_setprio 1
	s_waitcnt lgkmcnt(0)
	v_mfma_f32_16x16x32_bf16 v[122:125], v[130:133], v[162:165], v[122:125]
	v_mfma_f32_16x16x32_bf16 v[126:129], v[138:141], v[162:165], v[126:129]
	v_mfma_f32_16x16x32_bf16 v[106:109], v[130:133], v[184:187], v[106:109]
	v_mfma_f32_16x16x32_bf16 v[110:113], v[138:141], v[184:187], v[110:113]
	v_mfma_f32_16x16x32_bf16 v[90:93], v[130:133], v[192:195], v[90:93]
	v_mfma_f32_16x16x32_bf16 v[94:97], v[138:141], v[192:195], v[94:97]
	v_mfma_f32_16x16x32_bf16 v[74:77], v[130:133], v[200:203], v[74:77]
	v_mfma_f32_16x16x32_bf16 v[78:81], v[138:141], v[200:203], v[78:81]
	v_mfma_f32_16x16x32_bf16 v[122:125], v[134:137], v[166:169], v[122:125]
	v_mfma_f32_16x16x32_bf16 v[126:129], v[142:145], v[166:169], v[126:129]
	v_mfma_f32_16x16x32_bf16 v[106:109], v[134:137], v[188:191], v[106:109]
	v_mfma_f32_16x16x32_bf16 v[110:113], v[142:145], v[188:191], v[110:113]
	v_mfma_f32_16x16x32_bf16 v[90:93], v[134:137], v[196:199], v[90:93]
	v_mfma_f32_16x16x32_bf16 v[94:97], v[142:145], v[196:199], v[94:97]
	v_mfma_f32_16x16x32_bf16 v[74:77], v[134:137], v[214:217], v[74:77]
	v_mfma_f32_16x16x32_bf16 v[78:81], v[142:145], v[214:217], v[78:81]
	v_mfma_f32_16x16x32_bf16 v[114:117], v[146:149], v[162:165], v[114:117]
	v_mfma_f32_16x16x32_bf16 v[118:121], v[154:157], v[162:165], v[118:121]
	v_mfma_f32_16x16x32_bf16 v[98:101], v[146:149], v[184:187], v[98:101]
	v_mfma_f32_16x16x32_bf16 v[102:105], v[154:157], v[184:187], v[102:105]
	v_mfma_f32_16x16x32_bf16 v[82:85], v[146:149], v[192:195], v[82:85]
	v_mfma_f32_16x16x32_bf16 v[86:89], v[154:157], v[192:195], v[86:89]
	v_mfma_f32_16x16x32_bf16 v[66:69], v[146:149], v[200:203], v[66:69]
	v_mfma_f32_16x16x32_bf16 v[70:73], v[154:157], v[200:203], v[70:73]
	v_mfma_f32_16x16x32_bf16 v[114:117], v[150:153], v[166:169], v[114:117]
	v_mfma_f32_16x16x32_bf16 v[118:121], v[158:161], v[166:169], v[118:121]
	v_mfma_f32_16x16x32_bf16 v[98:101], v[150:153], v[188:191], v[98:101]
	v_mfma_f32_16x16x32_bf16 v[102:105], v[158:161], v[188:191], v[102:105]
	v_mfma_f32_16x16x32_bf16 v[82:85], v[150:153], v[196:199], v[82:85]
	v_mfma_f32_16x16x32_bf16 v[86:89], v[158:161], v[196:199], v[86:89]
	v_mfma_f32_16x16x32_bf16 v[66:69], v[150:153], v[214:217], v[66:69]
	v_mfma_f32_16x16x32_bf16 v[70:73], v[158:161], v[214:217], v[70:73]
	s_setprio 0
	s_barrier
	s_add_i32 m0, s45, s59
	ds_read_b128 v[162:165], v237 offset:49152
	ds_read_b128 v[166:169], v237 offset:50176
	ds_read_b128 v[184:187], v237 offset:51200
	ds_read_b128 v[188:191], v237 offset:52224
	ds_read_b128 v[192:195], v237 offset:53248
	ds_read_b128 v[196:199], v237 offset:54272
	ds_read_b128 v[200:203], v237 offset:55296
	ds_read_b128 v[214:217], v237 offset:56320
	global_load_lds_dwordx4 v204, vcc
	s_add_i32 m0, m0, 0x2000
	s_nop 0
	global_load_lds_dwordx4 v205, vcc
	s_add_i32 m0, s57, s59
	s_nop 0
	global_load_lds_dwordx4 v218, vcc
	s_add_i32 m0, m0, 0x2000
	s_nop 0
	global_load_lds_dwordx4 v219, vcc
	s_mov_b32 m0, s67
	s_nop 0
	global_load_lds_dwordx4 v220, s[14:15]
	s_mov_b32 m0, s7
	s_nop 0
	global_load_lds_dwordx4 v221, s[14:15]
	s_waitcnt vmcnt(8)
	s_waitcnt lgkmcnt(0)
	s_barrier
	s_setprio 1
	s_waitcnt lgkmcnt(0)
	v_mfma_f32_16x16x32_bf16 v[58:61], v[130:133], v[162:165], v[58:61]
	v_mfma_f32_16x16x32_bf16 v[62:65], v[138:141], v[162:165], v[62:65]
	v_mfma_f32_16x16x32_bf16 v[42:45], v[130:133], v[184:187], v[42:45]
	v_mfma_f32_16x16x32_bf16 v[46:49], v[138:141], v[184:187], v[46:49]
	v_mfma_f32_16x16x32_bf16 v[26:29], v[130:133], v[192:195], v[26:29]
	v_mfma_f32_16x16x32_bf16 v[30:33], v[138:141], v[192:195], v[30:33]
	v_mfma_f32_16x16x32_bf16 v[10:13], v[130:133], v[200:203], v[10:13]
	v_mfma_f32_16x16x32_bf16 v[14:17], v[138:141], v[200:203], v[14:17]
	v_mfma_f32_16x16x32_bf16 v[58:61], v[134:137], v[166:169], v[58:61]
	v_mfma_f32_16x16x32_bf16 v[62:65], v[142:145], v[166:169], v[62:65]
	v_mfma_f32_16x16x32_bf16 v[42:45], v[134:137], v[188:191], v[42:45]
	v_mfma_f32_16x16x32_bf16 v[46:49], v[142:145], v[188:191], v[46:49]
	v_mfma_f32_16x16x32_bf16 v[26:29], v[134:137], v[196:199], v[26:29]
	v_mfma_f32_16x16x32_bf16 v[30:33], v[142:145], v[196:199], v[30:33]
	v_mfma_f32_16x16x32_bf16 v[10:13], v[134:137], v[214:217], v[10:13]
	v_mfma_f32_16x16x32_bf16 v[14:17], v[142:145], v[214:217], v[14:17]
	v_mfma_f32_16x16x32_bf16 v[50:53], v[146:149], v[162:165], v[50:53]
	v_mfma_f32_16x16x32_bf16 v[54:57], v[154:157], v[162:165], v[54:57]
	v_mfma_f32_16x16x32_bf16 v[34:37], v[146:149], v[184:187], v[34:37]
	v_mfma_f32_16x16x32_bf16 v[38:41], v[154:157], v[184:187], v[38:41]
	v_mfma_f32_16x16x32_bf16 v[18:21], v[146:149], v[192:195], v[18:21]
	v_mfma_f32_16x16x32_bf16 v[22:25], v[154:157], v[192:195], v[22:25]
	v_mfma_f32_16x16x32_bf16 v[6:9], v[146:149], v[200:203], v[6:9]
	v_mfma_f32_16x16x32_bf16 v[2:5], v[154:157], v[200:203], v[2:5]
	v_mfma_f32_16x16x32_bf16 v[50:53], v[150:153], v[166:169], v[50:53]
	v_mfma_f32_16x16x32_bf16 v[54:57], v[158:161], v[166:169], v[54:57]
	v_mfma_f32_16x16x32_bf16 v[34:37], v[150:153], v[188:191], v[34:37]
	v_mfma_f32_16x16x32_bf16 v[38:41], v[158:161], v[188:191], v[38:41]
	v_mfma_f32_16x16x32_bf16 v[18:21], v[150:153], v[196:199], v[18:21]
	v_mfma_f32_16x16x32_bf16 v[22:25], v[158:161], v[196:199], v[22:25]
	v_mfma_f32_16x16x32_bf16 v[6:9], v[150:153], v[214:217], v[6:9]
	v_mfma_f32_16x16x32_bf16 v[2:5], v[158:161], v[214:217], v[2:5]
	s_setprio 0
	s_barrier
	s_add_u32 s0, s0, 0x100
	s_addc_u32 s1, s1, 0
	s_add_u32 s42, s42, 0x100
	s_addc_u32 s43, s43, 0
	s_cmp_ge_u32 s44, s61
	s_mov_b32 s14, s44
	s_cbranch_scc1 .Lk_exit
.LBB0_178:
	s_add_i32 s44, s14, 2
	s_add_u32 s45, s0, 0x80
	s_addc_u32 s15, s1, 0
	s_add_i32 s57, 0, 0x10000
	s_cmp_eq_u32 s18, s14
	s_cselect_b32 s15, s89, s15
	s_cselect_b32 s14, s88, s45
	s_cselect_b32 vcc_hi, s11, s43
	s_cselect_b32 vcc_lo, s10, s42
	s_add_i32 s45, 0, 0x14000
	s_waitcnt lgkmcnt(0)
	ds_read_b128 v[130:133], v248
	ds_read_b128 v[134:137], v248 offset:1024
	ds_read_b128 v[138:141], v248 offset:2048
	ds_read_b128 v[142:145], v248 offset:3072
	ds_read_b128 v[146:149], v248 offset:16384
	ds_read_b128 v[150:153], v248 offset:17408
	ds_read_b128 v[154:157], v248 offset:18432
	ds_read_b128 v[158:161], v248 offset:19456
	s_add_i32 m0, s70, 0xc000
	ds_read_b128 v[162:165], v237
	ds_read_b128 v[166:169], v237 offset:1024
	ds_read_b128 v[184:187], v237 offset:2048
	ds_read_b128 v[188:191], v237 offset:3072
	ds_read_b128 v[192:195], v237 offset:4096
	ds_read_b128 v[196:199], v237 offset:5120
	ds_read_b128 v[200:203], v237 offset:6144
	ds_read_b128 v[214:217], v237 offset:7168
	global_load_lds_dwordx4 v180, s[0:1]
	s_add_i32 m0, s70, 0xe000
	s_nop 0
	global_load_lds_dwordx4 v182, s[0:1]
	s_waitcnt vmcnt(8)
	s_waitcnt lgkmcnt(0)
	s_barrier
	s_setprio 1
	s_waitcnt lgkmcnt(0)
	v_mfma_f32_16x16x32_bf16 v[122:125], v[130:133], v[162:165], v[122:125]
	v_mfma_f32_16x16x32_bf16 v[126:129], v[138:141], v[162:165], v[126:129]
	v_mfma_f32_16x16x32_bf16 v[106:109], v[130:133], v[184:187], v[106:109]
	v_mfma_f32_16x16x32_bf16 v[110:113], v[138:141], v[184:187], v[110:113]
	v_mfma_f32_16x16x32_bf16 v[90:93], v[130:133], v[192:195], v[90:93]
	v_mfma_f32_16x16x32_bf16 v[94:97], v[138:141], v[192:195], v[94:97]
	v_mfma_f32_16x16x32_bf16 v[74:77], v[130:133], v[200:203], v[74:77]
	v_mfma_f32_16x16x32_bf16 v[78:81], v[138:141], v[200:203], v[78:81]
	v_mfma_f32_16x16x32_bf16 v[122:125], v[134:137], v[166:169], v[122:125]
	v_mfma_f32_16x16x32_bf16 v[126:129], v[142:145], v[166:169], v[126:129]
	v_mfma_f32_16x16x32_bf16 v[106:109], v[134:137], v[188:191], v[106:109]
	v_mfma_f32_16x16x32_bf16 v[110:113], v[142:145], v[188:191], v[110:113]
	v_mfma_f32_16x16x32_bf16 v[90:93], v[134:137], v[196:199], v[90:93]
	v_mfma_f32_16x16x32_bf16 v[94:97], v[142:145], v[196:199], v[94:97]
	v_mfma_f32_16x16x32_bf16 v[74:77], v[134:137], v[214:217], v[74:77]
	v_mfma_f32_16x16x32_bf16 v[78:81], v[142:145], v[214:217], v[78:81]
	v_mfma_f32_16x16x32_bf16 v[114:117], v[146:149], v[162:165], v[114:117]
	v_mfma_f32_16x16x32_bf16 v[118:121], v[154:157], v[162:165], v[118:121]
	v_mfma_f32_16x16x32_bf16 v[98:101], v[146:149], v[184:187], v[98:101]
	v_mfma_f32_16x16x32_bf16 v[102:105], v[154:157], v[184:187], v[102:105]
	v_mfma_f32_16x16x32_bf16 v[82:85], v[146:149], v[192:195], v[82:85]
	v_mfma_f32_16x16x32_bf16 v[86:89], v[154:157], v[192:195], v[86:89]
	v_mfma_f32_16x16x32_bf16 v[66:69], v[146:149], v[200:203], v[66:69]
	v_mfma_f32_16x16x32_bf16 v[70:73], v[154:157], v[200:203], v[70:73]
	v_mfma_f32_16x16x32_bf16 v[114:117], v[150:153], v[166:169], v[114:117]
	v_mfma_f32_16x16x32_bf16 v[118:121], v[158:161], v[166:169], v[118:121]
	v_mfma_f32_16x16x32_bf16 v[98:101], v[150:153], v[188:191], v[98:101]
	v_mfma_f32_16x16x32_bf16 v[102:105], v[158:161], v[188:191], v[102:105]
	v_mfma_f32_16x16x32_bf16 v[82:85], v[150:153], v[196:199], v[82:85]
	v_mfma_f32_16x16x32_bf16 v[86:89], v[158:161], v[196:199], v[86:89]
	v_mfma_f32_16x16x32_bf16 v[66:69], v[150:153], v[214:217], v[66:69]
	v_mfma_f32_16x16x32_bf16 v[70:73], v[158:161], v[214:217], v[70:73]
	s_setprio 0
	s_barrier
	s_add_i32 s57, s57, s59
	s_mov_b32 m0, s57
	ds_read_b128 v[162:165], v237 offset:16384
	ds_read_b128 v[166:169], v237 offset:17408
	ds_read_b128 v[184:187], v237 offset:18432
	ds_read_b128 v[188:191], v237 offset:19456
	ds_read_b128 v[192:195], v237 offset:20480
	ds_read_b128 v[196:199], v237 offset:21504
	ds_read_b128 v[200:203], v237 offset:22528
	ds_read_b128 v[214:217], v237 offset:23552
	global_load_lds_dwordx4 v0, vcc
	s_add_i32 m0, s57, 0x2000
	s_add_i32 s45, s45, s59
	global_load_lds_dwordx4 v176, vcc
	s_mov_b32 m0, s45
	s_nop 0
	global_load_lds_dwordx4 v242, vcc
	s_add_i32 m0, s45, 0x2000
	s_nop 0
	global_load_lds_dwordx4 v249, vcc
	s_mov_b32 m0, s70
	s_nop 0
	global_load_lds_dwordx4 v172, s[14:15]
	s_mov_b32 m0, s4
	s_nop 0
	global_load_lds_dwordx4 v174, s[14:15]
	s_waitcnt vmcnt(8)
	s_waitcnt lgkmcnt(0)
	s_barrier
	s_setprio 1
	s_waitcnt lgkmcnt(0)
	v_mfma_f32_16x16x32_bf16 v[58:61], v[130:133], v[162:165], v[58:61]
	v_mfma_f32_16x16x32_bf16 v[62:65], v[138:141], v[162:165], v[62:65]
	v_mfma_f32_16x16x32_bf16 v[42:45], v[130:133], v[184:187], v[42:45]
	v_mfma_f32_16x16x32_bf16 v[46:49], v[138:141], v[184:187], v[46:49]
	v_mfma_f32_16x16x32_bf16 v[26:29], v[130:133], v[192:195], v[26:29]
	v_mfma_f32_16x16x32_bf16 v[30:33], v[138:141], v[192:195], v[30:33]
	v_mfma_f32_16x16x32_bf16 v[10:13], v[130:133], v[200:203], v[10:13]
	v_mfma_f32_16x16x32_bf16 v[14:17], v[138:141], v[200:203], v[14:17]
	v_mfma_f32_16x16x32_bf16 v[58:61], v[134:137], v[166:169], v[58:61]
	v_mfma_f32_16x16x32_bf16 v[62:65], v[142:145], v[166:169], v[62:65]
	v_mfma_f32_16x16x32_bf16 v[42:45], v[134:137], v[188:191], v[42:45]
	v_mfma_f32_16x16x32_bf16 v[46:49], v[142:145], v[188:191], v[46:49]
	v_mfma_f32_16x16x32_bf16 v[26:29], v[134:137], v[196:199], v[26:29]
	v_mfma_f32_16x16x32_bf16 v[30:33], v[142:145], v[196:199], v[30:33]
	v_mfma_f32_16x16x32_bf16 v[10:13], v[134:137], v[214:217], v[10:13]
	v_mfma_f32_16x16x32_bf16 v[14:17], v[142:145], v[214:217], v[14:17]
	v_mfma_f32_16x16x32_bf16 v[50:53], v[146:149], v[162:165], v[50:53]
	v_mfma_f32_16x16x32_bf16 v[54:57], v[154:157], v[162:165], v[54:57]
	v_mfma_f32_16x16x32_bf16 v[34:37], v[146:149], v[184:187], v[34:37]
	v_mfma_f32_16x16x32_bf16 v[38:41], v[154:157], v[184:187], v[38:41]
	v_mfma_f32_16x16x32_bf16 v[18:21], v[146:149], v[192:195], v[18:21]
	v_mfma_f32_16x16x32_bf16 v[22:25], v[154:157], v[192:195], v[22:25]
	v_mfma_f32_16x16x32_bf16 v[6:9], v[146:149], v[200:203], v[6:9]
	v_mfma_f32_16x16x32_bf16 v[2:5], v[154:157], v[200:203], v[2:5]
	v_mfma_f32_16x16x32_bf16 v[50:53], v[150:153], v[166:169], v[50:53]
	v_mfma_f32_16x16x32_bf16 v[54:57], v[158:161], v[166:169], v[54:57]
	v_mfma_f32_16x16x32_bf16 v[34:37], v[150:153], v[188:191], v[34:37]
	v_mfma_f32_16x16x32_bf16 v[38:41], v[158:161], v[188:191], v[38:41]
	v_mfma_f32_16x16x32_bf16 v[18:21], v[150:153], v[196:199], v[18:21]
	v_mfma_f32_16x16x32_bf16 v[22:25], v[158:161], v[196:199], v[22:25]
	v_mfma_f32_16x16x32_bf16 v[6:9], v[150:153], v[214:217], v[6:9]
	v_mfma_f32_16x16x32_bf16 v[2:5], v[158:161], v[214:217], v[2:5]
	s_setprio 0
	s_barrier
	s_add_i32 s45, 0, 0x18000
	s_add_i32 s57, 0, 0x1c000
	ds_read_b128 v[130:133], v248 offset:32768
	ds_read_b128 v[134:137], v248 offset:33792
	ds_read_b128 v[138:141], v248 offset:34816
	ds_read_b128 v[142:145], v248 offset:35840
	ds_read_b128 v[146:149], v248 offset:49152
	ds_read_b128 v[150:153], v248 offset:50176
	ds_read_b128 v[154:157], v248 offset:51200
	ds_read_b128 v[158:161], v248 offset:52224
	s_mov_b32 m0, s63
	ds_read_b128 v[162:165], v237 offset:32768
	ds_read_b128 v[166:169], v237 offset:33792
	ds_read_b128 v[184:187], v237 offset:34816
	ds_read_b128 v[188:191], v237 offset:35840
	ds_read_b128 v[192:195], v237 offset:36864
	ds_read_b128 v[196:199], v237 offset:37888
	ds_read_b128 v[200:203], v237 offset:38912
	ds_read_b128 v[214:217], v237 offset:39936
	global_load_lds_dwordx4 v180, s[14:15]
	s_mov_b32 m0, s68
	s_nop 0
	global_load_lds_dwordx4 v182, s[14:15]
	s_waitcnt vmcnt(8)
	s_waitcnt lgkmcnt(0)
	s_barrier
	s_setprio 1
	s_waitcnt lgkmcnt(0)
	v_mfma_f32_16x16x32_bf16 v[122:125], v[130:133], v[162:165], v[122:125]
	v_mfma_f32_16x16x32_bf16 v[126:129], v[138:141], v[162:165], v[126:129]
	v_mfma_f32_16x16x32_bf16 v[106:109], v[130:133], v[184:187], v[106:109]
	v_mfma_f32_16x16x32_bf16 v[110:113], v[138:141], v[184:187], v[110:113]
	v_mfma_f32_16x16x32_bf16 v[90:93], v[130:133], v[192:195], v[90:93]
	v_mfma_f32_16x16x32_bf16 v[94:97], v[138:141], v[192:195], v[94:97]
	v_mfma_f32_16x16x32_bf16 v[74:77], v[130:133], v[200:203], v[74:77]
	v_mfma_f32_16x16x32_bf16 v[78:81], v[138:141], v[200:203], v[78:81]
	v_mfma_f32_16x16x32_bf16 v[122:125], v[134:137], v[166:169], v[122:125]
	v_mfma_f32_16x16x32_bf16 v[126:129], v[142:145], v[166:169], v[126:129]
	v_mfma_f32_16x16x32_bf16 v[106:109], v[134:137], v[188:191], v[106:109]
	v_mfma_f32_16x16x32_bf16 v[110:113], v[142:145], v[188:191], v[110:113]
	v_mfma_f32_16x16x32_bf16 v[90:93], v[134:137], v[196:199], v[90:93]
	v_mfma_f32_16x16x32_bf16 v[94:97], v[142:145], v[196:199], v[94:97]
	v_mfma_f32_16x16x32_bf16 v[74:77], v[134:137], v[214:217], v[74:77]
	v_mfma_f32_16x16x32_bf16 v[78:81], v[142:145], v[214:217], v[78:81]
	v_mfma_f32_16x16x32_bf16 v[114:117], v[146:149], v[162:165], v[114:117]
	v_mfma_f32_16x16x32_bf16 v[118:121], v[154:157], v[162:165], v[118:121]
	v_mfma_f32_16x16x32_bf16 v[98:101], v[146:149], v[184:187], v[98:101]
	v_mfma_f32_16x16x32_bf16 v[102:105], v[154:157], v[184:187], v[102:105]
	v_mfma_f32_16x16x32_bf16 v[82:85], v[146:149], v[192:195], v[82:85]
	v_mfma_f32_16x16x32_bf16 v[86:89], v[154:157], v[192:195], v[86:89]
	v_mfma_f32_16x16x32_bf16 v[66:69], v[146:149], v[200:203], v[66:69]
	v_mfma_f32_16x16x32_bf16 v[70:73], v[154:157], v[200:203], v[70:73]
	v_mfma_f32_16x16x32_bf16 v[114:117], v[150:153], v[166:169], v[114:117]
	v_mfma_f32_16x16x32_bf16 v[118:121], v[158:161], v[166:169], v[118:121]
	v_mfma_f32_16x16x32_bf16 v[98:101], v[150:153], v[188:191], v[98:101]
	v_mfma_f32_16x16x32_bf16 v[102:105], v[158:161], v[188:191], v[102:105]
	v_mfma_f32_16x16x32_bf16 v[82:85], v[150:153], v[196:199], v[82:85]
	v_mfma_f32_16x16x32_bf16 v[86:89], v[158:161], v[196:199], v[86:89]
	v_mfma_f32_16x16x32_bf16 v[66:69], v[150:153], v[214:217], v[66:69]
	v_mfma_f32_16x16x32_bf16 v[70:73], v[158:161], v[214:217], v[70:73]
	s_setprio 0
	s_barrier
	s_add_i32 m0, s45, s59
	ds_read_b128 v[162:165], v237 offset:49152
	ds_read_b128 v[166:169], v237 offset:50176
	ds_read_b128 v[184:187], v237 offset:51200
	ds_read_b128 v[188:191], v237 offset:52224
	ds_read_b128 v[192:195], v237 offset:53248
	ds_read_b128 v[196:199], v237 offset:54272
	ds_read_b128 v[200:203], v237 offset:55296
	ds_read_b128 v[214:217], v237 offset:56320
	global_load_lds_dwordx4 v204, vcc
	s_add_i32 m0, m0, 0x2000
	s_nop 0
	global_load_lds_dwordx4 v205, vcc
	s_add_i32 m0, s57, s59
	s_nop 0
	global_load_lds_dwordx4 v218, vcc
	s_add_i32 m0, m0, 0x2000
	s_nop 0
	global_load_lds_dwordx4 v219, vcc
	s_mov_b32 m0, s67
	s_nop 0
	global_load_lds_dwordx4 v220, s[14:15]
	s_mov_b32 m0, s7
	s_nop 0
	global_load_lds_dwordx4 v221, s[14:15]
	s_waitcnt vmcnt(8)
	s_waitcnt lgkmcnt(0)
	s_barrier
	s_setprio 1
	s_waitcnt lgkmcnt(0)
	v_mfma_f32_16x16x32_bf16 v[58:61], v[130:133], v[162:165], v[58:61]
	v_mfma_f32_16x16x32_bf16 v[62:65], v[138:141], v[162:165], v[62:65]
	v_mfma_f32_16x16x32_bf16 v[42:45], v[130:133], v[184:187], v[42:45]
	v_mfma_f32_16x16x32_bf16 v[46:49], v[138:141], v[184:187], v[46:49]
	v_mfma_f32_16x16x32_bf16 v[26:29], v[130:133], v[192:195], v[26:29]
	v_mfma_f32_16x16x32_bf16 v[30:33], v[138:141], v[192:195], v[30:33]
	v_mfma_f32_16x16x32_bf16 v[10:13], v[130:133], v[200:203], v[10:13]
	v_mfma_f32_16x16x32_bf16 v[14:17], v[138:141], v[200:203], v[14:17]
	v_mfma_f32_16x16x32_bf16 v[58:61], v[134:137], v[166:169], v[58:61]
	v_mfma_f32_16x16x32_bf16 v[62:65], v[142:145], v[166:169], v[62:65]
	v_mfma_f32_16x16x32_bf16 v[42:45], v[134:137], v[188:191], v[42:45]
	v_mfma_f32_16x16x32_bf16 v[46:49], v[142:145], v[188:191], v[46:49]
	v_mfma_f32_16x16x32_bf16 v[26:29], v[134:137], v[196:199], v[26:29]
	v_mfma_f32_16x16x32_bf16 v[30:33], v[142:145], v[196:199], v[30:33]
	v_mfma_f32_16x16x32_bf16 v[10:13], v[134:137], v[214:217], v[10:13]
	v_mfma_f32_16x16x32_bf16 v[14:17], v[142:145], v[214:217], v[14:17]
	v_mfma_f32_16x16x32_bf16 v[50:53], v[146:149], v[162:165], v[50:53]
	v_mfma_f32_16x16x32_bf16 v[54:57], v[154:157], v[162:165], v[54:57]
	v_mfma_f32_16x16x32_bf16 v[34:37], v[146:149], v[184:187], v[34:37]
	v_mfma_f32_16x16x32_bf16 v[38:41], v[154:157], v[184:187], v[38:41]
	v_mfma_f32_16x16x32_bf16 v[18:21], v[146:149], v[192:195], v[18:21]
	v_mfma_f32_16x16x32_bf16 v[22:25], v[154:157], v[192:195], v[22:25]
	v_mfma_f32_16x16x32_bf16 v[6:9], v[146:149], v[200:203], v[6:9]
	v_mfma_f32_16x16x32_bf16 v[2:5], v[154:157], v[200:203], v[2:5]
	v_mfma_f32_16x16x32_bf16 v[50:53], v[150:153], v[166:169], v[50:53]
	v_mfma_f32_16x16x32_bf16 v[54:57], v[158:161], v[166:169], v[54:57]
	v_mfma_f32_16x16x32_bf16 v[34:37], v[150:153], v[188:191], v[34:37]
	v_mfma_f32_16x16x32_bf16 v[38:41], v[158:161], v[188:191], v[38:41]
	v_mfma_f32_16x16x32_bf16 v[18:21], v[150:153], v[196:199], v[18:21]
	v_mfma_f32_16x16x32_bf16 v[22:25], v[158:161], v[196:199], v[22:25]
	v_mfma_f32_16x16x32_bf16 v[6:9], v[150:153], v[214:217], v[6:9]
	v_mfma_f32_16x16x32_bf16 v[2:5], v[158:161], v[214:217], v[2:5]
	s_setprio 0
	s_barrier
	s_add_u32 s0, s0, 0x100
	s_addc_u32 s1, s1, 0
	s_add_u32 s42, s42, 0x100
	s_addc_u32 s43, s43, 0
	s_cmp_ge_u32 s44, s61
	s_mov_b32 s14, s44
	s_cbranch_scc0 .LBB0_178
